# P6 K loop: one static s_setprio 1 for the wave group that arrives second (wr=1, raised after its extra start barrier, cleared at the epilogue), tail flips removed
# speedup vs baseline: 1.0018x; 1.0018x over previous
.LBB0_2356:
	s_ashr_i32 s38, s58, 3
	s_add_i32 s38, s59, s38
	s_mul_hi_i32 s39, s38, 0x2e8ba2e9
	s_lshr_b32 s58, s39, 31
	s_ashr_i32 s65, s39, 5
	s_add_i32 s65, s65, s58
	s_lshl_b32 s85, s65, 3
	s_sub_i32 s39, 0x41, s85
	s_min_u32 s58, s39, 8
	s_mul_i32 s39, s65, 0xb0
	s_sub_i32 s59, s38, s39
	s_sext_i32_i16 s38, s59
	v_cvt_f32_ubyte0_e32 v3, s58
	v_cvt_f32_i32_e32 v2, s38
	v_rcp_iflag_f32_e32 v4, v3
	s_ashr_i32 s38, s38, 30
	s_or_b32 s60, s38, 1
	v_readfirstlane_b32 s61, v188
	v_mul_f32_e32 v4, v2, v4
	v_trunc_f32_e32 v4, v4
	v_fma_f32 v2, -v4, v3, v2
	v_cvt_i32_f32_e32 v4, v4
	v_cmp_ge_f32_e64 s[38:39], |v2|, v3
	s_and_b64 s[38:39], s[38:39], exec
	s_cselect_b32 s38, s60, 0
	v_readfirstlane_b32 s39, v4
	s_add_i32 s38, s39, s38
	s_sext_i32_i16 s64, s38
	s_mul_i32 s38, s38, s58
	s_sub_i32 s38, s59, s38
	s_sext_i32_i16 s66, s38
	s_lshl_b32 s58, s64, 8
	s_add_i32 s85, s85, s66
	s_ashr_i32 s59, s58, 31
	s_lshl_b32 s60, s85, 8
	v_and_b32_e32 v20, 0xff, v0
	v_lshlrev_b32_e32 v20, 2, v20
	s_lshl_b32 s38, s60, 2
	v_add_u32_e32 v21, s38, v20
	global_load_dword v22, v21, s[12:13]
	s_lshl_b64 s[38:39], s[58:59], 11
	s_add_u32 s62, s97, s38
	s_addc_u32 s63, s2, s39
	v_lshl_add_u64 v[4:5], s[62:63], 0, v[164:165]
	s_mov_b32 m0, s61
	v_readfirstlane_b32 s61, v189
	global_load_lds_dwordx4 v[4:5], off
	s_mov_b32 m0, s61
	s_ashr_i32 s61, s60, 31
	v_lshl_add_u64 v[2:3], s[62:63], 0, v[162:163]
	s_lshl_b64 s[62:63], s[60:61], 11
	s_add_u32 s62, s94, s62
	s_addc_u32 s63, s95, s63
	v_lshl_add_u64 v[8:9], s[62:63], 0, v[164:165]
	v_lshl_add_u64 v[6:7], s[62:63], 0, v[162:163]
	s_or_b32 s62, s58, 0x80
	s_ashr_i32 s63, s62, 31
	s_lshl_b64 s[62:63], s[62:63], 11
	s_add_u32 s62, s97, s62
	s_addc_u32 s63, s2, s63
	v_readfirstlane_b32 s61, v183
	v_lshl_add_u64 v[12:13], s[62:63], 0, v[164:165]
	v_lshl_add_u64 v[10:11], s[62:63], 0, v[162:163]
	s_or_b32 s62, s60, 0x80
	global_load_lds_dwordx4 v[2:3], off
	s_mov_b32 m0, s61
	v_readfirstlane_b32 s61, v184
	s_ashr_i32 s63, s62, 31
	global_load_lds_dwordx4 v[8:9], off
	s_mov_b32 m0, s61
	v_readfirstlane_b32 s61, v190
	s_lshl_b64 s[62:63], s[62:63], 11
	global_load_lds_dwordx4 v[6:7], off
	s_mov_b32 m0, s61
	v_readfirstlane_b32 s61, v191
	s_add_u32 s62, s94, s62
	global_load_lds_dwordx4 v[12:13], off
	s_mov_b32 m0, s61
	s_addc_u32 s63, s95, s63
	v_readfirstlane_b32 s61, v185
	global_load_lds_dwordx4 v[10:11], off
	v_lshl_add_u64 v[130:131], s[62:63], 0, v[164:165]
	s_mov_b32 m0, s61
	v_readfirstlane_b32 s61, v186
	global_load_lds_dwordx4 v[130:131], off
	v_lshl_add_u64 v[132:133], s[62:63], 0, v[162:163]
	s_mov_b32 m0, s61
	s_nop 0
	global_load_lds_dwordx4 v[132:133], off
	s_and_saveexec_b64 s[62:63], s[0:1]
	s_cbranch_execz .LBB0_2358
	s_barrier
	s_setprio 1

.LBB0_2359:
	ds_read_b128 v[150:153], v192
	ds_read_b128 v[154:157], v192 offset:1024
	ds_read_b128 v[158:161], v192 offset:2048
	ds_read_b128 v[172:175], v192 offset:3072
	v_add_u32_e32 v148, 0xc000, v183
	v_lshl_add_u64 v[180:181], s[62:63], 0, v[138:139]
	v_readfirstlane_b32 s61, v148
	v_add_u32_e32 v149, 0xe000, v183
	v_lshl_add_u64 v[230:231], v[180:181], 0, s[18:19]
	s_mov_b32 m0, s61
	v_lshl_add_u64 v[246:247], s[62:63], 0, v[140:141]
	v_readfirstlane_b32 s61, v149
	ds_read_b128 v[176:179], v193
	ds_read_b128 v[202:205], v193 offset:1024
	ds_read_b128 v[206:209], v194
	ds_read_b128 v[210:213], v194 offset:1024
	ds_read_b128 v[214:217], v195
	ds_read_b128 v[218:221], v195 offset:1024
	ds_read_b128 v[222:225], v196
	ds_read_b128 v[226:229], v196 offset:1024
	global_load_lds_dwordx4 v[230:231], off
	v_lshl_add_u64 v[230:231], v[246:247], 0, s[18:19]
	s_mov_b32 m0, s61
	s_nop 0
	global_load_lds_dwordx4 v[230:231], off
	s_waitcnt lgkmcnt(8)
	s_barrier
	s_waitcnt lgkmcnt(0)
	s_waitcnt lgkmcnt(0)
	v_mfma_f32_16x16x32_bf16 v[126:129], v[150:153], v[176:179], v[126:129]
	v_mfma_f32_16x16x32_bf16 v[122:125], v[158:161], v[176:179], v[122:125]
	v_mfma_f32_16x16x32_bf16 v[118:121], v[150:153], v[206:209], v[118:121]
	v_mfma_f32_16x16x32_bf16 v[114:117], v[158:161], v[206:209], v[114:117]
	v_mfma_f32_16x16x32_bf16 v[110:113], v[150:153], v[214:217], v[110:113]
	v_mfma_f32_16x16x32_bf16 v[106:109], v[158:161], v[214:217], v[106:109]
	v_mfma_f32_16x16x32_bf16 v[102:105], v[150:153], v[222:225], v[102:105]
	v_mfma_f32_16x16x32_bf16 v[98:101], v[158:161], v[222:225], v[98:101]
	v_mfma_f32_16x16x32_bf16 v[126:129], v[154:157], v[202:205], v[126:129]
	v_mfma_f32_16x16x32_bf16 v[122:125], v[172:175], v[202:205], v[122:125]
	v_mfma_f32_16x16x32_bf16 v[118:121], v[154:157], v[210:213], v[118:121]
	v_mfma_f32_16x16x32_bf16 v[114:117], v[172:175], v[210:213], v[114:117]
	v_mfma_f32_16x16x32_bf16 v[110:113], v[154:157], v[218:221], v[110:113]
	v_mfma_f32_16x16x32_bf16 v[106:109], v[172:175], v[218:221], v[106:109]
	v_mfma_f32_16x16x32_bf16 v[102:105], v[154:157], v[226:229], v[102:105]
	v_mfma_f32_16x16x32_bf16 v[98:101], v[172:175], v[226:229], v[98:101]
	s_barrier
	v_lshl_add_u64 v[248:249], s[62:63], 0, v[134:135]
	v_readfirstlane_b32 s61, v188
	v_lshl_add_u64 v[250:251], v[248:249], 0, s[20:21]
	s_mov_b32 m0, s61
	ds_read_b128 v[230:233], v197
	ds_read_b128 v[234:237], v197 offset:1024
	ds_read_b128 v[238:241], v197 offset:2048
	ds_read_b128 v[242:245], v197 offset:3072
	global_load_lds_dwordx4 v[250:251], off
	v_lshl_add_u64 v[250:251], s[62:63], 0, v[136:137]
	v_readfirstlane_b32 s61, v189
	v_lshl_add_u64 v[252:253], v[250:251], 0, s[20:21]
	s_mov_b32 m0, s61
	s_nop 0
	global_load_lds_dwordx4 v[252:253], off
	s_barrier
	s_waitcnt lgkmcnt(0)
	s_waitcnt lgkmcnt(0)
	v_mfma_f32_16x16x32_bf16 v[94:97], v[230:233], v[176:179], v[94:97]
	v_mfma_f32_16x16x32_bf16 v[90:93], v[238:241], v[176:179], v[90:93]
	v_mfma_f32_16x16x32_bf16 v[86:89], v[230:233], v[206:209], v[86:89]
	v_mfma_f32_16x16x32_bf16 v[82:85], v[238:241], v[206:209], v[82:85]
	v_mfma_f32_16x16x32_bf16 v[78:81], v[230:233], v[214:217], v[78:81]
	v_mfma_f32_16x16x32_bf16 v[74:77], v[238:241], v[214:217], v[74:77]
	v_mfma_f32_16x16x32_bf16 v[70:73], v[230:233], v[222:225], v[70:73]
	v_mfma_f32_16x16x32_bf16 v[66:69], v[238:241], v[222:225], v[66:69]
	v_mfma_f32_16x16x32_bf16 v[94:97], v[234:237], v[202:205], v[94:97]
	v_mfma_f32_16x16x32_bf16 v[90:93], v[242:245], v[202:205], v[90:93]
	v_mfma_f32_16x16x32_bf16 v[86:89], v[234:237], v[210:213], v[86:89]
	v_mfma_f32_16x16x32_bf16 v[82:85], v[242:245], v[210:213], v[82:85]
	v_mfma_f32_16x16x32_bf16 v[78:81], v[234:237], v[218:221], v[78:81]
	v_mfma_f32_16x16x32_bf16 v[74:77], v[242:245], v[218:221], v[74:77]
	v_mfma_f32_16x16x32_bf16 v[70:73], v[234:237], v[226:229], v[70:73]
	v_mfma_f32_16x16x32_bf16 v[66:69], v[242:245], v[226:229], v[66:69]
	v_readfirstlane_b32 s61, v183
	v_lshl_add_u64 v[252:253], v[180:181], 0, s[22:23]
	s_mov_b32 m0, s61
	v_readfirstlane_b32 s61, v184
	s_barrier
	ds_read_b128 v[176:179], v193 offset:16384
	ds_read_b128 v[202:205], v193 offset:17408
	ds_read_b128 v[206:209], v194 offset:16384
	ds_read_b128 v[210:213], v194 offset:17408
	ds_read_b128 v[214:217], v195 offset:16384
	ds_read_b128 v[218:221], v195 offset:17408
	ds_read_b128 v[222:225], v196 offset:16384
	ds_read_b128 v[226:229], v196 offset:17408
	global_load_lds_dwordx4 v[252:253], off
	v_lshl_add_u64 v[252:253], v[246:247], 0, s[22:23]
	s_mov_b32 m0, s61
	s_nop 0
	global_load_lds_dwordx4 v[252:253], off
	s_barrier
	s_waitcnt lgkmcnt(0)
	s_waitcnt lgkmcnt(0)
	v_mfma_f32_16x16x32_bf16 v[62:65], v[150:153], v[176:179], v[62:65]
	v_mfma_f32_16x16x32_bf16 v[58:61], v[158:161], v[176:179], v[58:61]
	v_mfma_f32_16x16x32_bf16 v[54:57], v[150:153], v[206:209], v[54:57]
	v_mfma_f32_16x16x32_bf16 v[50:53], v[158:161], v[206:209], v[50:53]
	v_mfma_f32_16x16x32_bf16 v[46:49], v[150:153], v[214:217], v[46:49]
	v_mfma_f32_16x16x32_bf16 v[42:45], v[158:161], v[214:217], v[42:45]
	v_mfma_f32_16x16x32_bf16 v[38:41], v[150:153], v[222:225], v[38:41]
	v_mfma_f32_16x16x32_bf16 v[34:37], v[158:161], v[222:225], v[34:37]
	v_mfma_f32_16x16x32_bf16 v[62:65], v[154:157], v[202:205], v[62:65]
	v_mfma_f32_16x16x32_bf16 v[58:61], v[172:175], v[202:205], v[58:61]
	v_mfma_f32_16x16x32_bf16 v[54:57], v[154:157], v[210:213], v[54:57]
	v_mfma_f32_16x16x32_bf16 v[50:53], v[172:175], v[210:213], v[50:53]
	v_mfma_f32_16x16x32_bf16 v[46:49], v[154:157], v[218:221], v[46:49]
	v_mfma_f32_16x16x32_bf16 v[42:45], v[172:175], v[218:221], v[42:45]
	v_mfma_f32_16x16x32_bf16 v[38:41], v[154:157], v[226:229], v[38:41]
	v_mfma_f32_16x16x32_bf16 v[34:37], v[172:175], v[226:229], v[34:37]
	s_barrier
	v_readfirstlane_b32 s61, v190
	v_lshl_add_u64 v[150:151], v[248:249], 0, s[24:25]
	s_mov_b32 m0, s61
	v_readfirstlane_b32 s61, v191
	global_load_lds_dwordx4 v[150:151], off
	v_lshl_add_u64 v[150:151], v[250:251], 0, s[24:25]
	s_mov_b32 m0, s61
	s_nop 0
	global_load_lds_dwordx4 v[150:151], off
	s_waitcnt vmcnt(6)
	s_barrier
	v_mfma_f32_16x16x32_bf16 v[30:33], v[230:233], v[176:179], v[30:33]
	v_mfma_f32_16x16x32_bf16 v[26:29], v[238:241], v[176:179], v[26:29]
	v_mfma_f32_16x16x32_bf16 v[22:25], v[230:233], v[206:209], v[22:25]
	v_mfma_f32_16x16x32_bf16 v[18:21], v[238:241], v[206:209], v[18:21]
	v_mfma_f32_16x16x32_bf16 v[14:17], v[230:233], v[214:217], v[14:17]
	v_mfma_f32_16x16x32_bf16 v[10:13], v[238:241], v[214:217], v[10:13]
	v_mfma_f32_16x16x32_bf16 v[6:9], v[230:233], v[222:225], v[6:9]
	v_mfma_f32_16x16x32_bf16 v[2:5], v[238:241], v[222:225], v[2:5]
	v_mfma_f32_16x16x32_bf16 v[30:33], v[234:237], v[202:205], v[30:33]
	v_mfma_f32_16x16x32_bf16 v[26:29], v[242:245], v[202:205], v[26:29]
	v_mfma_f32_16x16x32_bf16 v[22:25], v[234:237], v[210:213], v[22:25]
	v_mfma_f32_16x16x32_bf16 v[18:21], v[242:245], v[210:213], v[18:21]
	v_mfma_f32_16x16x32_bf16 v[14:17], v[234:237], v[218:221], v[14:17]
	v_mfma_f32_16x16x32_bf16 v[10:13], v[242:245], v[218:221], v[10:13]
	v_mfma_f32_16x16x32_bf16 v[6:9], v[234:237], v[226:229], v[6:9]
	v_mfma_f32_16x16x32_bf16 v[2:5], v[242:245], v[226:229], v[2:5]
	s_barrier
	ds_read_b128 v[150:153], v199
	ds_read_b128 v[154:157], v199 offset:1024
	ds_read_b128 v[158:161], v199 offset:2048
	ds_read_b128 v[172:175], v199 offset:3072
	v_readfirstlane_b32 s61, v185
	v_lshl_add_u64 v[230:231], v[180:181], 0, s[26:27]
	s_mov_b32 m0, s61
	v_readfirstlane_b32 s61, v186
	ds_read_b128 v[176:179], v193 offset:32768
	ds_read_b128 v[202:205], v193 offset:33792
	ds_read_b128 v[206:209], v194 offset:32768
	ds_read_b128 v[210:213], v194 offset:33792
	ds_read_b128 v[214:217], v195 offset:32768
	ds_read_b128 v[218:221], v195 offset:33792
	ds_read_b128 v[222:225], v196 offset:32768
	ds_read_b128 v[226:229], v196 offset:33792
	global_load_lds_dwordx4 v[230:231], off
	v_lshl_add_u64 v[230:231], v[246:247], 0, s[26:27]
	s_mov_b32 m0, s61
	s_nop 0
	global_load_lds_dwordx4 v[230:231], off
	s_waitcnt lgkmcnt(8)
	s_barrier
	s_waitcnt lgkmcnt(0)
	s_waitcnt lgkmcnt(0)
	v_mfma_f32_16x16x32_bf16 v[126:129], v[150:153], v[176:179], v[126:129]
	v_mfma_f32_16x16x32_bf16 v[122:125], v[158:161], v[176:179], v[122:125]
	v_mfma_f32_16x16x32_bf16 v[118:121], v[150:153], v[206:209], v[118:121]
	v_mfma_f32_16x16x32_bf16 v[114:117], v[158:161], v[206:209], v[114:117]
	v_mfma_f32_16x16x32_bf16 v[110:113], v[150:153], v[214:217], v[110:113]
	v_mfma_f32_16x16x32_bf16 v[106:109], v[158:161], v[214:217], v[106:109]
	v_mfma_f32_16x16x32_bf16 v[102:105], v[150:153], v[222:225], v[102:105]
	v_mfma_f32_16x16x32_bf16 v[98:101], v[158:161], v[222:225], v[98:101]
	v_mfma_f32_16x16x32_bf16 v[126:129], v[154:157], v[202:205], v[126:129]
	v_mfma_f32_16x16x32_bf16 v[122:125], v[172:175], v[202:205], v[122:125]
	v_mfma_f32_16x16x32_bf16 v[118:121], v[154:157], v[210:213], v[118:121]
	v_mfma_f32_16x16x32_bf16 v[114:117], v[172:175], v[210:213], v[114:117]
	v_mfma_f32_16x16x32_bf16 v[110:113], v[154:157], v[218:221], v[110:113]
	v_mfma_f32_16x16x32_bf16 v[106:109], v[172:175], v[218:221], v[106:109]
	v_mfma_f32_16x16x32_bf16 v[102:105], v[154:157], v[226:229], v[102:105]
	v_mfma_f32_16x16x32_bf16 v[98:101], v[172:175], v[226:229], v[98:101]
	s_barrier
	v_readfirstlane_b32 s61, v142
	v_lshl_add_u64 v[252:253], v[248:249], 0, s[28:29]
	s_mov_b32 m0, s61
	v_readfirstlane_b32 s61, v143
	ds_read_b128 v[230:233], v200
	ds_read_b128 v[234:237], v200 offset:1024
	ds_read_b128 v[238:241], v200 offset:2048
	ds_read_b128 v[242:245], v200 offset:3072
	global_load_lds_dwordx4 v[252:253], off
	v_lshl_add_u64 v[252:253], v[250:251], 0, s[28:29]
	s_mov_b32 m0, s61
	s_nop 0
	global_load_lds_dwordx4 v[252:253], off
	s_barrier
	s_waitcnt lgkmcnt(0)
	s_waitcnt lgkmcnt(0)
	v_mfma_f32_16x16x32_bf16 v[94:97], v[230:233], v[176:179], v[94:97]
	v_mfma_f32_16x16x32_bf16 v[90:93], v[238:241], v[176:179], v[90:93]
	v_mfma_f32_16x16x32_bf16 v[86:89], v[230:233], v[206:209], v[86:89]
	v_mfma_f32_16x16x32_bf16 v[82:85], v[238:241], v[206:209], v[82:85]
	v_mfma_f32_16x16x32_bf16 v[78:81], v[230:233], v[214:217], v[78:81]
	v_mfma_f32_16x16x32_bf16 v[74:77], v[238:241], v[214:217], v[74:77]
	v_mfma_f32_16x16x32_bf16 v[70:73], v[230:233], v[222:225], v[70:73]
	v_mfma_f32_16x16x32_bf16 v[66:69], v[238:241], v[222:225], v[66:69]
	v_mfma_f32_16x16x32_bf16 v[94:97], v[234:237], v[202:205], v[94:97]
	v_mfma_f32_16x16x32_bf16 v[90:93], v[242:245], v[202:205], v[90:93]
	v_mfma_f32_16x16x32_bf16 v[86:89], v[234:237], v[210:213], v[86:89]
	v_mfma_f32_16x16x32_bf16 v[82:85], v[242:245], v[210:213], v[82:85]
	v_mfma_f32_16x16x32_bf16 v[78:81], v[234:237], v[218:221], v[78:81]
	v_mfma_f32_16x16x32_bf16 v[74:77], v[242:245], v[218:221], v[74:77]
	v_mfma_f32_16x16x32_bf16 v[70:73], v[234:237], v[226:229], v[70:73]
	v_mfma_f32_16x16x32_bf16 v[66:69], v[242:245], v[226:229], v[66:69]
	v_readfirstlane_b32 s61, v144
	v_lshl_add_u64 v[180:181], v[180:181], 0, s[30:31]
	s_mov_b32 m0, s61
	v_readfirstlane_b32 s61, v145
	s_barrier
	ds_read_b128 v[176:179], v193 offset:49152
	ds_read_b128 v[202:205], v193 offset:50176
	ds_read_b128 v[206:209], v194 offset:49152
	ds_read_b128 v[210:213], v194 offset:50176
	ds_read_b128 v[214:217], v195 offset:49152
	ds_read_b128 v[218:221], v195 offset:50176
	ds_read_b128 v[222:225], v196 offset:49152
	ds_read_b128 v[226:229], v196 offset:50176
	global_load_lds_dwordx4 v[180:181], off
	v_lshl_add_u64 v[180:181], v[246:247], 0, s[30:31]
	s_mov_b32 m0, s61
	s_nop 0
	global_load_lds_dwordx4 v[180:181], off
	s_barrier
	s_waitcnt lgkmcnt(0)
	s_waitcnt lgkmcnt(0)
	v_mfma_f32_16x16x32_bf16 v[62:65], v[150:153], v[176:179], v[62:65]
	v_mfma_f32_16x16x32_bf16 v[58:61], v[158:161], v[176:179], v[58:61]
	v_mfma_f32_16x16x32_bf16 v[54:57], v[150:153], v[206:209], v[54:57]
	v_mfma_f32_16x16x32_bf16 v[50:53], v[158:161], v[206:209], v[50:53]
	v_mfma_f32_16x16x32_bf16 v[46:49], v[150:153], v[214:217], v[46:49]
	v_mfma_f32_16x16x32_bf16 v[42:45], v[158:161], v[214:217], v[42:45]
	v_mfma_f32_16x16x32_bf16 v[38:41], v[150:153], v[222:225], v[38:41]
	v_mfma_f32_16x16x32_bf16 v[34:37], v[158:161], v[222:225], v[34:37]
	v_mfma_f32_16x16x32_bf16 v[62:65], v[154:157], v[202:205], v[62:65]
	v_mfma_f32_16x16x32_bf16 v[58:61], v[172:175], v[202:205], v[58:61]
	v_mfma_f32_16x16x32_bf16 v[54:57], v[154:157], v[210:213], v[54:57]
	v_mfma_f32_16x16x32_bf16 v[50:53], v[172:175], v[210:213], v[50:53]
	v_mfma_f32_16x16x32_bf16 v[46:49], v[154:157], v[218:221], v[46:49]
	v_mfma_f32_16x16x32_bf16 v[42:45], v[172:175], v[218:221], v[42:45]
	v_mfma_f32_16x16x32_bf16 v[38:41], v[154:157], v[226:229], v[38:41]
	v_mfma_f32_16x16x32_bf16 v[34:37], v[172:175], v[226:229], v[34:37]
	s_barrier
	v_readfirstlane_b32 s61, v146
	v_lshl_add_u64 v[150:151], v[248:249], 0, s[34:35]
	s_mov_b32 m0, s61
	v_readfirstlane_b32 s61, v147
	global_load_lds_dwordx4 v[150:151], off
	v_lshl_add_u64 v[150:151], v[250:251], 0, s[34:35]
	s_mov_b32 m0, s61
	s_nop 0
	global_load_lds_dwordx4 v[150:151], off
	s_waitcnt vmcnt(6)
	s_barrier
	v_mfma_f32_16x16x32_bf16 v[30:33], v[230:233], v[176:179], v[30:33]
	v_mfma_f32_16x16x32_bf16 v[26:29], v[238:241], v[176:179], v[26:29]
	v_mfma_f32_16x16x32_bf16 v[22:25], v[230:233], v[206:209], v[22:25]
	v_mfma_f32_16x16x32_bf16 v[18:21], v[238:241], v[206:209], v[18:21]
	v_mfma_f32_16x16x32_bf16 v[14:17], v[230:233], v[214:217], v[14:17]
	v_mfma_f32_16x16x32_bf16 v[10:13], v[238:241], v[214:217], v[10:13]
	v_mfma_f32_16x16x32_bf16 v[6:9], v[230:233], v[222:225], v[6:9]
	v_mfma_f32_16x16x32_bf16 v[2:5], v[238:241], v[222:225], v[2:5]
	v_mfma_f32_16x16x32_bf16 v[30:33], v[234:237], v[202:205], v[30:33]
	v_mfma_f32_16x16x32_bf16 v[26:29], v[242:245], v[202:205], v[26:29]
	v_mfma_f32_16x16x32_bf16 v[22:25], v[234:237], v[210:213], v[22:25]
	v_mfma_f32_16x16x32_bf16 v[18:21], v[242:245], v[210:213], v[18:21]
	v_mfma_f32_16x16x32_bf16 v[14:17], v[234:237], v[218:221], v[14:17]
	v_mfma_f32_16x16x32_bf16 v[10:13], v[242:245], v[218:221], v[10:13]
	v_mfma_f32_16x16x32_bf16 v[6:9], v[234:237], v[226:229], v[6:9]
	v_mfma_f32_16x16x32_bf16 v[2:5], v[242:245], v[226:229], v[2:5]
	s_add_i32 s39, s39, 2
	s_add_u32 s62, s62, 0x100
	s_addc_u32 s63, s63, 0
	s_cmp_lt_u32 s39, 12
	s_barrier
	s_cbranch_scc1 .LBB0_2359
	v_readfirstlane_b32 s39, v148
	v_lshl_add_u64 v[130:131], v[130:131], 0, s[36:37]
	s_mov_b32 m0, s39
	v_readfirstlane_b32 s39, v149
	ds_read_b128 v[134:137], v192
	ds_read_b128 v[138:141], v192 offset:1024
	ds_read_b128 v[142:145], v192 offset:2048
	ds_read_b128 v[150:153], v192 offset:3072
	ds_read_b128 v[154:157], v193
	ds_read_b128 v[158:161], v193 offset:1024
	ds_read_b128 v[172:175], v194
	ds_read_b128 v[176:179], v194 offset:1024
	ds_read_b128 v[202:205], v195
	ds_read_b128 v[206:209], v195 offset:1024
	ds_read_b128 v[210:213], v196
	ds_read_b128 v[214:217], v196 offset:1024
	global_load_lds_dwordx4 v[130:131], off
	v_lshl_add_u64 v[130:131], v[132:133], 0, s[36:37]
	s_mov_b32 m0, s39
	s_nop 0
	global_load_lds_dwordx4 v[130:131], off
	s_barrier
	s_waitcnt lgkmcnt(0)
	s_waitcnt lgkmcnt(0)
	v_mfma_f32_16x16x32_bf16 v[126:129], v[134:137], v[154:157], v[126:129]
	v_mfma_f32_16x16x32_bf16 v[122:125], v[142:145], v[154:157], v[122:125]
	v_mfma_f32_16x16x32_bf16 v[118:121], v[134:137], v[172:175], v[118:121]
	v_mfma_f32_16x16x32_bf16 v[114:117], v[142:145], v[172:175], v[114:117]
	v_mfma_f32_16x16x32_bf16 v[110:113], v[134:137], v[202:205], v[110:113]
	v_mfma_f32_16x16x32_bf16 v[106:109], v[142:145], v[202:205], v[106:109]
	v_mfma_f32_16x16x32_bf16 v[102:105], v[134:137], v[210:213], v[102:105]
	v_mfma_f32_16x16x32_bf16 v[98:101], v[142:145], v[210:213], v[98:101]
	v_mfma_f32_16x16x32_bf16 v[126:129], v[138:141], v[158:161], v[126:129]
	v_mfma_f32_16x16x32_bf16 v[122:125], v[150:153], v[158:161], v[122:125]
	v_mfma_f32_16x16x32_bf16 v[118:121], v[138:141], v[176:179], v[118:121]
	v_mfma_f32_16x16x32_bf16 v[114:117], v[150:153], v[176:179], v[114:117]
	v_mfma_f32_16x16x32_bf16 v[110:113], v[138:141], v[206:209], v[110:113]
	v_mfma_f32_16x16x32_bf16 v[106:109], v[150:153], v[206:209], v[106:109]
	v_mfma_f32_16x16x32_bf16 v[102:105], v[138:141], v[214:217], v[102:105]
	v_mfma_f32_16x16x32_bf16 v[98:101], v[150:153], v[214:217], v[98:101]
	s_barrier
	ds_read_b128 v[130:133], v197
	ds_read_b128 v[146:149], v197 offset:1024
	ds_read_b128 v[218:221], v197 offset:2048
	ds_read_b128 v[222:225], v197 offset:3072
	s_barrier
	s_waitcnt lgkmcnt(0)
	s_waitcnt lgkmcnt(0)
	v_mfma_f32_16x16x32_bf16 v[94:97], v[130:133], v[154:157], v[94:97]
	v_mfma_f32_16x16x32_bf16 v[90:93], v[218:221], v[154:157], v[90:93]
	v_mfma_f32_16x16x32_bf16 v[86:89], v[130:133], v[172:175], v[86:89]
	v_mfma_f32_16x16x32_bf16 v[82:85], v[218:221], v[172:175], v[82:85]
	v_mfma_f32_16x16x32_bf16 v[78:81], v[130:133], v[202:205], v[78:81]
	v_mfma_f32_16x16x32_bf16 v[74:77], v[218:221], v[202:205], v[74:77]
	v_mfma_f32_16x16x32_bf16 v[70:73], v[130:133], v[210:213], v[70:73]
	v_mfma_f32_16x16x32_bf16 v[66:69], v[218:221], v[210:213], v[66:69]
	v_mfma_f32_16x16x32_bf16 v[94:97], v[146:149], v[158:161], v[94:97]
	v_mfma_f32_16x16x32_bf16 v[90:93], v[222:225], v[158:161], v[90:93]
	v_mfma_f32_16x16x32_bf16 v[86:89], v[146:149], v[176:179], v[86:89]
	v_mfma_f32_16x16x32_bf16 v[82:85], v[222:225], v[176:179], v[82:85]
	v_mfma_f32_16x16x32_bf16 v[78:81], v[146:149], v[206:209], v[78:81]
	v_mfma_f32_16x16x32_bf16 v[74:77], v[222:225], v[206:209], v[74:77]
	v_mfma_f32_16x16x32_bf16 v[70:73], v[146:149], v[214:217], v[70:73]
	v_mfma_f32_16x16x32_bf16 v[66:69], v[222:225], v[214:217], v[66:69]
	s_barrier
	ds_read_b128 v[154:157], v193 offset:16384
	ds_read_b128 v[158:161], v193 offset:17408
	ds_read_b128 v[172:175], v194 offset:16384
	ds_read_b128 v[176:179], v194 offset:17408
	ds_read_b128 v[202:205], v195 offset:16384
	ds_read_b128 v[206:209], v195 offset:17408
	ds_read_b128 v[210:213], v196 offset:16384
	ds_read_b128 v[214:217], v196 offset:17408
	s_waitcnt vmcnt(4)
	s_barrier
	s_waitcnt lgkmcnt(0)
	s_waitcnt lgkmcnt(0)
	v_mfma_f32_16x16x32_bf16 v[62:65], v[134:137], v[154:157], v[62:65]
	v_mfma_f32_16x16x32_bf16 v[58:61], v[142:145], v[154:157], v[58:61]
	v_mfma_f32_16x16x32_bf16 v[54:57], v[134:137], v[172:175], v[54:57]
	v_mfma_f32_16x16x32_bf16 v[50:53], v[142:145], v[172:175], v[50:53]
	v_mfma_f32_16x16x32_bf16 v[46:49], v[134:137], v[202:205], v[46:49]
	v_mfma_f32_16x16x32_bf16 v[42:45], v[142:145], v[202:205], v[42:45]
	v_mfma_f32_16x16x32_bf16 v[38:41], v[134:137], v[210:213], v[38:41]
	v_mfma_f32_16x16x32_bf16 v[34:37], v[142:145], v[210:213], v[34:37]
	v_mfma_f32_16x16x32_bf16 v[62:65], v[138:141], v[158:161], v[62:65]
	v_mfma_f32_16x16x32_bf16 v[58:61], v[150:153], v[158:161], v[58:61]
	v_mfma_f32_16x16x32_bf16 v[54:57], v[138:141], v[176:179], v[54:57]
	v_mfma_f32_16x16x32_bf16 v[50:53], v[150:153], v[176:179], v[50:53]
	v_mfma_f32_16x16x32_bf16 v[46:49], v[138:141], v[206:209], v[46:49]
	v_mfma_f32_16x16x32_bf16 v[42:45], v[150:153], v[206:209], v[42:45]
	v_mfma_f32_16x16x32_bf16 v[38:41], v[138:141], v[214:217], v[38:41]
	v_mfma_f32_16x16x32_bf16 v[34:37], v[150:153], v[214:217], v[34:37]
	v_mfma_f32_16x16x32_bf16 v[30:33], v[130:133], v[154:157], v[30:33]
	v_mfma_f32_16x16x32_bf16 v[26:29], v[218:221], v[154:157], v[26:29]
	v_mfma_f32_16x16x32_bf16 v[22:25], v[130:133], v[172:175], v[22:25]
	v_mfma_f32_16x16x32_bf16 v[18:21], v[218:221], v[172:175], v[18:21]
	v_mfma_f32_16x16x32_bf16 v[14:17], v[130:133], v[202:205], v[14:17]
	v_mfma_f32_16x16x32_bf16 v[10:13], v[218:221], v[202:205], v[10:13]
	v_mfma_f32_16x16x32_bf16 v[6:9], v[130:133], v[210:213], v[6:9]
	v_mfma_f32_16x16x32_bf16 v[2:5], v[218:221], v[210:213], v[2:5]
	v_mfma_f32_16x16x32_bf16 v[30:33], v[146:149], v[158:161], v[30:33]
	v_mfma_f32_16x16x32_bf16 v[26:29], v[222:225], v[158:161], v[26:29]
	v_mfma_f32_16x16x32_bf16 v[22:25], v[146:149], v[176:179], v[22:25]
	v_mfma_f32_16x16x32_bf16 v[18:21], v[222:225], v[176:179], v[18:21]
	v_mfma_f32_16x16x32_bf16 v[14:17], v[146:149], v[206:209], v[14:17]
	v_mfma_f32_16x16x32_bf16 v[10:13], v[222:225], v[206:209], v[10:13]
	v_mfma_f32_16x16x32_bf16 v[6:9], v[146:149], v[214:217], v[6:9]
	v_mfma_f32_16x16x32_bf16 v[2:5], v[222:225], v[214:217], v[2:5]
	s_barrier
	ds_read_b128 v[172:175], v199
	ds_read_b128 v[176:179], v199 offset:1024
	ds_read_b128 v[202:205], v199 offset:2048
	ds_read_b128 v[206:209], v199 offset:3072
	ds_read_b128 v[130:133], v193 offset:32768
	ds_read_b128 v[134:137], v193 offset:33792
	ds_read_b128 v[210:213], v194 offset:32768
	ds_read_b128 v[214:217], v194 offset:33792
	ds_read_b128 v[218:221], v195 offset:32768
	ds_read_b128 v[222:225], v195 offset:33792
	ds_read_b128 v[226:229], v196 offset:32768
	ds_read_b128 v[230:233], v196 offset:33792
	s_waitcnt vmcnt(2)
	s_barrier
	s_waitcnt lgkmcnt(0)
	s_waitcnt lgkmcnt(0)
	v_mfma_f32_16x16x32_bf16 v[126:129], v[172:175], v[130:133], v[126:129]
	v_mfma_f32_16x16x32_bf16 v[122:125], v[202:205], v[130:133], v[122:125]
	v_mfma_f32_16x16x32_bf16 v[118:121], v[172:175], v[210:213], v[118:121]
	v_mfma_f32_16x16x32_bf16 v[114:117], v[202:205], v[210:213], v[114:117]
	v_mfma_f32_16x16x32_bf16 v[110:113], v[172:175], v[218:221], v[110:113]
	v_mfma_f32_16x16x32_bf16 v[106:109], v[202:205], v[218:221], v[106:109]
	v_mfma_f32_16x16x32_bf16 v[102:105], v[172:175], v[226:229], v[102:105]
	v_mfma_f32_16x16x32_bf16 v[98:101], v[202:205], v[226:229], v[98:101]
	v_mfma_f32_16x16x32_bf16 v[158:161], v[176:179], v[134:137], v[126:129]
	v_mfma_f32_16x16x32_bf16 v[154:157], v[206:209], v[134:137], v[122:125]
	v_mfma_f32_16x16x32_bf16 v[142:145], v[176:179], v[214:217], v[118:121]
	v_mfma_f32_16x16x32_bf16 v[138:141], v[206:209], v[214:217], v[114:117]
	v_mfma_f32_16x16x32_bf16 v[126:129], v[176:179], v[222:225], v[110:113]
	v_mfma_f32_16x16x32_bf16 v[122:125], v[206:209], v[222:225], v[106:109]
	v_mfma_f32_16x16x32_bf16 v[110:113], v[176:179], v[230:233], v[102:105]
	v_mfma_f32_16x16x32_bf16 v[106:109], v[206:209], v[230:233], v[98:101]
	s_barrier
	ds_read_b128 v[234:237], v200
	ds_read_b128 v[238:241], v200 offset:1024
	ds_read_b128 v[242:245], v200 offset:2048
	ds_read_b128 v[246:249], v200 offset:3072
	s_waitcnt vmcnt(0)
	s_barrier
	s_waitcnt lgkmcnt(0)
	s_waitcnt lgkmcnt(0)
	v_mfma_f32_16x16x32_bf16 v[94:97], v[234:237], v[130:133], v[94:97]
	v_mfma_f32_16x16x32_bf16 v[90:93], v[242:245], v[130:133], v[90:93]
	v_mfma_f32_16x16x32_bf16 v[86:89], v[234:237], v[210:213], v[86:89]
	v_mfma_f32_16x16x32_bf16 v[82:85], v[242:245], v[210:213], v[82:85]
	v_mfma_f32_16x16x32_bf16 v[78:81], v[234:237], v[218:221], v[78:81]
	v_mfma_f32_16x16x32_bf16 v[74:77], v[242:245], v[218:221], v[74:77]
	v_mfma_f32_16x16x32_bf16 v[70:73], v[234:237], v[226:229], v[70:73]
	v_mfma_f32_16x16x32_bf16 v[66:69], v[242:245], v[226:229], v[66:69]
	v_mfma_f32_16x16x32_bf16 v[150:153], v[238:241], v[134:137], v[94:97]
	v_mfma_f32_16x16x32_bf16 v[146:149], v[246:249], v[134:137], v[90:93]
	v_mfma_f32_16x16x32_bf16 v[134:137], v[238:241], v[214:217], v[86:89]
	v_mfma_f32_16x16x32_bf16 v[130:133], v[246:249], v[214:217], v[82:85]
	v_mfma_f32_16x16x32_bf16 v[118:121], v[238:241], v[222:225], v[78:81]
	v_mfma_f32_16x16x32_bf16 v[114:117], v[246:249], v[222:225], v[74:77]
	v_mfma_f32_16x16x32_bf16 v[102:105], v[238:241], v[230:233], v[70:73]
	v_mfma_f32_16x16x32_bf16 v[98:101], v[246:249], v[230:233], v[66:69]
	s_barrier
	s_nop 0
	ds_read_b128 v[66:69], v193 offset:49152
	ds_read_b128 v[70:73], v193 offset:50176
	ds_read_b128 v[210:213], v194 offset:49152
	ds_read_b128 v[214:217], v194 offset:50176
	ds_read_b128 v[218:221], v195 offset:49152
	ds_read_b128 v[222:225], v195 offset:50176
	ds_read_b128 v[226:229], v196 offset:49152
	ds_read_b128 v[230:233], v196 offset:50176
	s_barrier
	s_waitcnt lgkmcnt(0)
	s_waitcnt lgkmcnt(0)
	v_mfma_f32_16x16x32_bf16 v[62:65], v[172:175], v[66:69], v[62:65]
	v_mfma_f32_16x16x32_bf16 v[58:61], v[202:205], v[66:69], v[58:61]
	v_mfma_f32_16x16x32_bf16 v[54:57], v[172:175], v[210:213], v[54:57]
	v_mfma_f32_16x16x32_bf16 v[50:53], v[202:205], v[210:213], v[50:53]
	v_mfma_f32_16x16x32_bf16 v[46:49], v[172:175], v[218:221], v[46:49]
	v_mfma_f32_16x16x32_bf16 v[42:45], v[202:205], v[218:221], v[42:45]
	v_mfma_f32_16x16x32_bf16 v[38:41], v[172:175], v[226:229], v[38:41]
	v_mfma_f32_16x16x32_bf16 v[34:37], v[202:205], v[226:229], v[34:37]
	v_mfma_f32_16x16x32_bf16 v[94:97], v[176:179], v[70:73], v[62:65]
	v_mfma_f32_16x16x32_bf16 v[90:93], v[206:209], v[70:73], v[58:61]
	v_mfma_f32_16x16x32_bf16 v[78:81], v[176:179], v[214:217], v[54:57]
	v_mfma_f32_16x16x32_bf16 v[74:77], v[206:209], v[214:217], v[50:53]
	v_mfma_f32_16x16x32_bf16 v[62:65], v[176:179], v[222:225], v[46:49]
	v_mfma_f32_16x16x32_bf16 v[58:61], v[206:209], v[222:225], v[42:45]
	v_mfma_f32_16x16x32_bf16 v[46:49], v[176:179], v[230:233], v[38:41]
	v_mfma_f32_16x16x32_bf16 v[42:45], v[206:209], v[230:233], v[34:37]
	v_mfma_f32_16x16x32_bf16 v[30:33], v[234:237], v[66:69], v[30:33]
	v_mfma_f32_16x16x32_bf16 v[26:29], v[242:245], v[66:69], v[26:29]
	v_mfma_f32_16x16x32_bf16 v[22:25], v[234:237], v[210:213], v[22:25]
	v_mfma_f32_16x16x32_bf16 v[18:21], v[242:245], v[210:213], v[18:21]
	v_mfma_f32_16x16x32_bf16 v[14:17], v[234:237], v[218:221], v[14:17]
	v_mfma_f32_16x16x32_bf16 v[10:13], v[242:245], v[218:221], v[10:13]
	v_mfma_f32_16x16x32_bf16 v[6:9], v[234:237], v[226:229], v[6:9]
	v_mfma_f32_16x16x32_bf16 v[2:5], v[242:245], v[226:229], v[2:5]
	v_mfma_f32_16x16x32_bf16 v[86:89], v[238:241], v[70:73], v[30:33]
	v_mfma_f32_16x16x32_bf16 v[82:85], v[246:249], v[70:73], v[26:29]
	v_mfma_f32_16x16x32_bf16 v[70:73], v[238:241], v[214:217], v[22:25]
	v_mfma_f32_16x16x32_bf16 v[66:69], v[246:249], v[214:217], v[18:21]
	v_mfma_f32_16x16x32_bf16 v[54:57], v[238:241], v[222:225], v[14:17]
	v_mfma_f32_16x16x32_bf16 v[50:53], v[246:249], v[222:225], v[10:13]
	v_mfma_f32_16x16x32_bf16 v[38:41], v[238:241], v[230:233], v[6:9]
	v_mfma_f32_16x16x32_bf16 v[34:37], v[246:249], v[230:233], v[2:5]
	s_barrier
	s_and_saveexec_b64 s[62:63], s[6:7]
	s_cbranch_execz .LBB0_2362
	s_barrier
.LBB0_2362:
	s_setprio 0
	s_or_b64 exec, exec, s[62:63]
	v_mov_b32_e32 v166, v0
	v_mov_b32_e32 v202, v0
	s_lshl_b32 s62, s64, 7
	v_lshlrev_b32_e32 v203, 2, v202
	v_and_b32_e32 v201, 0x7c, v203
	v_or_b32_e32 v172, s62, v201
	v_ashrrev_i32_e32 v173, 31, v172
	v_lshlrev_b64 v[10:11], 2, v[172:173]
	v_lshl_add_u64 v[2:3], s[50:51], 0, v[10:11]
	v_add_co_u32_e32 v6, vcc, 0x2000, v2
	v_lshl_add_u64 v[26:27], s[48:49], 0, v[10:11]
	s_nop 0
	v_addc_co_u32_e32 v7, vcc, 0, v3, vcc
	v_add_co_u32_e32 v14, vcc, 0x2000, v26
	v_ashrrev_i32_e32 v174, 2, v166
	s_nop 0
	v_addc_co_u32_e32 v15, vcc, 0, v27, vcc
	v_add_co_u32_e32 v18, vcc, 0x5000, v26
	v_and_b32_e32 v174, 0xffffffc0, v174
	s_nop 0
	v_addc_co_u32_e32 v19, vcc, 0, v27, vcc
	v_add_co_u32_e32 v22, vcc, 0x8000, v26
	v_and_b32_e32 v204, 15, v166
	s_nop 0
	v_addc_co_u32_e32 v23, vcc, 0, v27, vcc
	v_add_co_u32_e32 v28, vcc, 0xb000, v26
	v_add_u32_e32 v205, s60, v174
	s_nop 0
	v_addc_co_u32_e32 v29, vcc, 0, v27, vcc
	v_or_b32_e32 v176, v205, v204
	v_add_co_u32_e32 v30, vcc, 0xd000, v26
	v_ashrrev_i32_e32 v177, 31, v176
	v_add_u32_e32 v174, 0x80, v176
	v_addc_co_u32_e32 v31, vcc, 0, v27, vcc
	v_subrev_u32_e32 v178, s60, v176
	v_lshlrev_b32_e32 v178, 2, v178
	v_add_u32_e32 v178, 0x20010, v178
	v_ashrrev_i32_e32 v175, 31, v174
	global_load_dwordx4 v[2:5], v[2:3], off
	s_nop 0
	global_load_dwordx4 v[6:9], v[6:7], off offset:3072
	s_nop 0
	global_load_dwordx4 v[10:13], v[26:27], off
	s_nop 0
	global_load_dwordx4 v[14:17], v[14:15], off offset:3072
	s_nop 0
	global_load_dwordx4 v[18:21], v[18:19], off offset:2048
	s_nop 0
	global_load_dwordx4 v[22:25], v[22:23], off offset:1024
	s_nop 0
	global_load_dwordx4 v[26:29], v[28:29], off
	s_nop 0
	global_load_dwordx4 v[30:33], v[30:31], off offset:3072
	v_lshl_add_u64 v[180:181], v[174:175], 2, s[12:13]
	ds_read_b32 v174, v178
	ds_read_b32 v213, v178 offset:64
	ds_read_b32 v212, v178 offset:128
	ds_read_b32 v211, v178 offset:192
	ds_read_b32 v210, v178 offset:512
	ds_read_b32 v209, v178 offset:576
	ds_read_b32 v208, v178 offset:640
	ds_read_b32 v177, v178 offset:704
	v_subrev_co_u32_e32 v207, vcc, 14, v204
	s_xor_b64 s[64:65], vcc, -1
	v_cmp_lt_i32_e32 vcc, s75, v176
	s_and_b64 s[68:69], vcc, s[64:65]
	v_mov_b64_e32 v[178:179], 0
	s_and_saveexec_b64 s[66:67], s[68:69]
	v_add_u32_e32 v175, 0xffffc000, v205
	v_lshrrev_b32_e32 v175, 3, v175
	v_add_u32_e32 v175, v175, v207
	v_mov_b64_e32 v[178:179], s[8:9]
	v_mad_u64_u32 v[178:179], s[68:69], v175, s76, v[178:179]
	s_or_b64 exec, exec, s[66:67]
	s_waitcnt lgkmcnt(0)
	s_barrier
	v_fmamk_f32 v174, v174, 0x3a800000, v187
	v_mul_f32_e32 v175, 0x4b800000, v174
	v_cmp_gt_f32_e32 vcc, s77, v174
	s_movk_i32 s39, 0x60
	s_nop 0
	v_cndmask_b32_e32 v174, v174, v175, vcc
	v_rsq_f32_e32 v174, v174
	v_lshrrev_b32_e32 v175, 1, v166
	v_lshrrev_b32_e32 v166, 2, v166
	v_and_b32_e32 v166, 12, v166
	v_mul_f32_e32 v180, 0x45800000, v174
	v_cndmask_b32_e32 v180, v174, v180, vcc
	v_subrev_u32_e32 v174, s60, v176
	v_mul_lo_u32 v181, v174, s78
	v_and_or_b32 v166, v175, s39, v166
	v_add_u32_e32 v215, 16, v181
	v_lshlrev_b32_e32 v206, 1, v166
	v_pk_mul_f32 v[158:159], v[158:159], v[180:181] op_sel_hi:[1,0]
	v_add_u32_e32 v214, v215, v206
	v_cvt_pk_bf16_f32 v174, v158, v159
	v_pk_mul_f32 v[160:161], v[160:161], v[180:181] op_sel_hi:[1,0]
	v_cmp_ne_u64_e32 vcc, 0, v[178:179]
	v_cvt_pk_bf16_f32 v175, v160, v161
	ds_write_b64 v214, v[174:175]
	v_or_b32_e32 v174, s62, v166
	v_ashrrev_i32_e32 v175, 31, v174
	s_and_saveexec_b64 s[66:67], vcc
	s_cbranch_execz .LBB0_2366
	v_lshl_add_u64 v[216:217], v[174:175], 2, v[178:179]
	global_store_dwordx4 v[216:217], v[158:161], off
